# P11 token-shift mixes: the 6 mu vectors loaded once per column half instead of inside 16 serialised 6-iteration load/wait/store loops
# speedup vs baseline: 1.0121x; 1.0121x over previous
.LBB0_924:
	v_mov_b32_e32 v150, v101
	v_mov_b32_e32 v151, v102
	s_waitcnt lgkmcnt(10)
	v_pk_add_f32 v[92:93], v[150:151], v[92:93]
	s_mov_b32 s38, 0x3a000000
	s_waitcnt lgkmcnt(9)
	v_pk_add_f32 v[92:93], v[92:93], v[146:147]
	s_ashr_i32 s53, s52, 31
	s_waitcnt lgkmcnt(8)
	v_pk_add_f32 v[92:93], v[92:93], v[96:97]
	s_lshl_b64 s[70:71], s[52:53], 12
	v_pk_fma_f32 v[146:147], v[92:93], s[38:39], v[142:143] op_sel_hi:[1,0,0]
	s_ashr_i32 s59, s58, 31
	v_mul_f32_e32 v92, 0x4b800000, v146
	v_cmp_gt_f32_e64 s[42:43], s5, v146
	v_lshl_add_u64 v[128:129], v[118:119], 0, s[10:11]
	v_mov_b32_e32 v101, v100
	v_cndmask_b32_e64 v92, v146, v92, s[42:43]
	v_rsq_f32_e32 v92, v92
	s_xor_b64 s[64:65], s[8:9], -1
	v_cmp_gt_f32_e32 vcc, s5, v147
	s_mov_b64 s[8:9], 8
	v_mul_f32_e32 v93, 0x45800000, v92
	v_cndmask_b32_e64 v92, v92, v93, s[42:43]
	v_mov_b32_e32 v93, v92
	v_pk_mul_f32 v[72:73], v[72:73], v[92:93] op_sel_hi:[1,0]
	s_nop 0
	v_pk_mul_f32 v[72:73], v[0:1], v[72:73]
	s_waitcnt vmcnt(1)
	v_pk_fma_f32 v[96:97], v[124:125], v[72:73], v[88:89]
	v_pk_mul_f32 v[72:73], v[74:75], v[92:93] op_sel_hi:[1,0]
	s_waitcnt vmcnt(0)
	v_pk_add_f32 v[74:75], v[76:77], v[96:97] neg_lo:[0,1] neg_hi:[0,1]
	v_pk_mul_f32 v[72:73], v[2:3], v[72:73]
	s_nop 0
	v_pk_fma_f32 v[102:103], v[126:127], v[72:73], v[90:91]
	v_lshl_add_u64 v[72:73], v[112:113], 0, s[70:71]
	v_pk_add_f32 v[76:77], v[78:79], v[102:103] neg_lo:[0,1] neg_hi:[0,1]
	s_mov_b64 s[8:9], 0
	global_load_dwordx4 v[178:181], v[108:109], off
	s_add_u32 s8, s8, 0x2000
	v_lshl_add_u64 v[202:203], v[108:109], 0, s[8:9]
	global_load_dwordx4 v[182:185], v[202:203], off
	s_add_u32 s8, s8, 0x2000
	v_lshl_add_u64 v[202:203], v[108:109], 0, s[8:9]
	global_load_dwordx4 v[186:189], v[202:203], off
	s_add_u32 s8, s8, 0x2000
	v_lshl_add_u64 v[202:203], v[108:109], 0, s[8:9]
	global_load_dwordx4 v[190:193], v[202:203], off
	s_add_u32 s8, s8, 0x2000
	v_lshl_add_u64 v[202:203], v[108:109], 0, s[8:9]
	global_load_dwordx4 v[194:197], v[202:203], off
	s_add_u32 s8, s8, 0x2000
	v_lshl_add_u64 v[202:203], v[108:109], 0, s[8:9]
	global_load_dwordx4 v[198:201], v[202:203], off
	s_waitcnt vmcnt(0)
	v_pk_fma_f32 v[78:79], v[74:75], v[178:179], v[96:97]
	v_pk_fma_f32 v[150:151], v[76:77], v[180:181], v[102:103]
	v_cvt_pk_bf16_f32 v78, v78, v79
	v_cvt_pk_bf16_f32 v79, v150, v151
	global_store_dwordx2 v[72:73], v[78:79], off offset:-4
	v_lshl_add_u64 v[72:73], v[72:73], 0, s[12:13]
	v_pk_fma_f32 v[78:79], v[74:75], v[182:183], v[96:97]
	v_pk_fma_f32 v[150:151], v[76:77], v[184:185], v[102:103]
	v_cvt_pk_bf16_f32 v78, v78, v79
	v_cvt_pk_bf16_f32 v79, v150, v151
	global_store_dwordx2 v[72:73], v[78:79], off offset:-4
	v_lshl_add_u64 v[72:73], v[72:73], 0, s[12:13]
	v_pk_fma_f32 v[78:79], v[74:75], v[186:187], v[96:97]
	v_pk_fma_f32 v[150:151], v[76:77], v[188:189], v[102:103]
	v_cvt_pk_bf16_f32 v78, v78, v79
	v_cvt_pk_bf16_f32 v79, v150, v151
	global_store_dwordx2 v[72:73], v[78:79], off offset:-4
	v_lshl_add_u64 v[72:73], v[72:73], 0, s[12:13]
	v_pk_fma_f32 v[78:79], v[74:75], v[190:191], v[96:97]
	v_pk_fma_f32 v[150:151], v[76:77], v[192:193], v[102:103]
	v_cvt_pk_bf16_f32 v78, v78, v79
	v_cvt_pk_bf16_f32 v79, v150, v151
	global_store_dwordx2 v[72:73], v[78:79], off offset:-4
	v_lshl_add_u64 v[72:73], v[72:73], 0, s[12:13]
	v_pk_fma_f32 v[78:79], v[74:75], v[194:195], v[96:97]
	v_pk_fma_f32 v[150:151], v[76:77], v[196:197], v[102:103]
	v_cvt_pk_bf16_f32 v78, v78, v79
	v_cvt_pk_bf16_f32 v79, v150, v151
	global_store_dwordx2 v[72:73], v[78:79], off offset:-4
	v_lshl_add_u64 v[72:73], v[72:73], 0, s[12:13]
	v_pk_fma_f32 v[78:79], v[74:75], v[198:199], v[96:97]
	v_pk_fma_f32 v[150:151], v[76:77], v[200:201], v[102:103]
	v_cvt_pk_bf16_f32 v78, v78, v79
	v_cvt_pk_bf16_f32 v79, v150, v151
	global_store_dwordx2 v[72:73], v[78:79], off offset:-4
	v_lshl_add_u64 v[72:73], v[72:73], 0, s[12:13]
	v_mul_f32_e32 v72, 0x4b800000, v147
	v_cndmask_b32_e32 v72, v147, v72, vcc
	v_rsq_f32_e32 v72, v72
	s_ashr_i32 s47, s46, 31
	s_lshl_b64 s[8:9], s[46:47], 12
	s_mov_b64 s[38:39], s[90:91]
	v_mul_f32_e32 v73, 0x45800000, v72
	v_cndmask_b32_e32 v72, v72, v73, vcc
	v_mov_b32_e32 v73, v72
	v_pk_mul_f32 v[68:69], v[68:69], v[72:73] op_sel_hi:[1,0]
	v_pk_mul_f32 v[70:71], v[70:71], v[72:73] op_sel_hi:[1,0]
	v_pk_mul_f32 v[68:69], v[0:1], v[68:69]
	v_pk_mul_f32 v[74:75], v[2:3], v[70:71]
	v_pk_fma_f32 v[70:71], v[124:125], v[68:69], v[88:89]
	v_pk_fma_f32 v[74:75], v[126:127], v[74:75], v[90:91]
	v_lshl_add_u64 v[68:69], v[112:113], 0, s[8:9]
	v_pk_add_f32 v[76:77], v[96:97], v[70:71] neg_lo:[0,1] neg_hi:[0,1]
	v_pk_add_f32 v[78:79], v[102:103], v[74:75] neg_lo:[0,1] neg_hi:[0,1]
	s_mov_b64 s[42:43], 8
	v_pk_fma_f32 v[96:97], v[76:77], v[178:179], v[70:71]
	v_pk_fma_f32 v[102:103], v[78:79], v[180:181], v[74:75]
	v_cvt_pk_bf16_f32 v96, v96, v97
	v_cvt_pk_bf16_f32 v97, v102, v103
	global_store_dwordx2 v[68:69], v[96:97], off offset:-4
	v_lshl_add_u64 v[68:69], v[68:69], 0, s[12:13]
	v_pk_fma_f32 v[96:97], v[76:77], v[182:183], v[70:71]
	v_pk_fma_f32 v[102:103], v[78:79], v[184:185], v[74:75]
	v_cvt_pk_bf16_f32 v96, v96, v97
	v_cvt_pk_bf16_f32 v97, v102, v103
	global_store_dwordx2 v[68:69], v[96:97], off offset:-4
	v_lshl_add_u64 v[68:69], v[68:69], 0, s[12:13]
	v_pk_fma_f32 v[96:97], v[76:77], v[186:187], v[70:71]
	v_pk_fma_f32 v[102:103], v[78:79], v[188:189], v[74:75]
	v_cvt_pk_bf16_f32 v96, v96, v97
	v_cvt_pk_bf16_f32 v97, v102, v103
	global_store_dwordx2 v[68:69], v[96:97], off offset:-4
	v_lshl_add_u64 v[68:69], v[68:69], 0, s[12:13]
	v_pk_fma_f32 v[96:97], v[76:77], v[190:191], v[70:71]
	v_pk_fma_f32 v[102:103], v[78:79], v[192:193], v[74:75]
	v_cvt_pk_bf16_f32 v96, v96, v97
	v_cvt_pk_bf16_f32 v97, v102, v103
	global_store_dwordx2 v[68:69], v[96:97], off offset:-4
	v_lshl_add_u64 v[68:69], v[68:69], 0, s[12:13]
	v_pk_fma_f32 v[96:97], v[76:77], v[194:195], v[70:71]
	v_pk_fma_f32 v[102:103], v[78:79], v[196:197], v[74:75]
	v_cvt_pk_bf16_f32 v96, v96, v97
	v_cvt_pk_bf16_f32 v97, v102, v103
	global_store_dwordx2 v[68:69], v[96:97], off offset:-4
	v_lshl_add_u64 v[68:69], v[68:69], 0, s[12:13]
	v_pk_fma_f32 v[96:97], v[76:77], v[198:199], v[70:71]
	v_pk_fma_f32 v[102:103], v[78:79], v[200:201], v[74:75]
	v_cvt_pk_bf16_f32 v96, v96, v97
	v_cvt_pk_bf16_f32 v97, v102, v103
	global_store_dwordx2 v[68:69], v[96:97], off offset:-4
	v_lshl_add_u64 v[68:69], v[68:69], 0, s[12:13]
	s_waitcnt lgkmcnt(7)
	v_pk_add_f32 v[68:69], v[134:135], v[94:95]
	s_mov_b32 s42, 0x3a000000
	s_waitcnt lgkmcnt(6)
	v_pk_add_f32 v[68:69], v[68:69], v[144:145]
	s_ashr_i32 s45, s44, 31
	v_pk_add_f32 v[68:69], v[68:69], v[98:99]
	s_lshl_b64 s[90:91], s[44:45], 12
	v_pk_fma_f32 v[94:95], v[68:69], s[42:43], v[142:143] op_sel_hi:[1,0,0]
	s_nop 0
	v_mul_f32_e32 v68, 0x4b800000, v94
	v_cmp_gt_f32_e64 s[42:43], s5, v94
	v_cmp_gt_f32_e32 vcc, s5, v95
	s_nop 0
	v_cndmask_b32_e64 v68, v94, v68, s[42:43]
	v_rsq_f32_e32 v68, v68
	s_nop 0
	v_mul_f32_e32 v69, 0x45800000, v68
	v_cndmask_b32_e64 v68, v68, v69, s[42:43]
	v_mov_b32_e32 v69, v68
	v_pk_mul_f32 v[64:65], v[64:65], v[68:69] op_sel_hi:[1,0]
	v_pk_mul_f32 v[66:67], v[66:67], v[68:69] op_sel_hi:[1,0]
	v_pk_mul_f32 v[64:65], v[0:1], v[64:65]
	s_mov_b64 s[42:43], 8
	v_pk_fma_f32 v[76:77], v[124:125], v[64:65], v[88:89]
	v_pk_mul_f32 v[64:65], v[2:3], v[66:67]
	v_pk_add_f32 v[66:67], v[70:71], v[76:77] neg_lo:[0,1] neg_hi:[0,1]
	v_pk_fma_f32 v[78:79], v[126:127], v[64:65], v[90:91]
	v_lshl_add_u64 v[64:65], v[112:113], 0, s[90:91]
	v_pk_add_f32 v[70:71], v[74:75], v[78:79] neg_lo:[0,1] neg_hi:[0,1]
	v_pk_fma_f32 v[74:75], v[66:67], v[178:179], v[76:77]
	v_pk_fma_f32 v[96:97], v[70:71], v[180:181], v[78:79]
	v_cvt_pk_bf16_f32 v74, v74, v75
	v_cvt_pk_bf16_f32 v75, v96, v97
	global_store_dwordx2 v[64:65], v[74:75], off offset:-4
	v_lshl_add_u64 v[64:65], v[64:65], 0, s[12:13]
	v_pk_fma_f32 v[74:75], v[66:67], v[182:183], v[76:77]
	v_pk_fma_f32 v[96:97], v[70:71], v[184:185], v[78:79]
	v_cvt_pk_bf16_f32 v74, v74, v75
	v_cvt_pk_bf16_f32 v75, v96, v97
	global_store_dwordx2 v[64:65], v[74:75], off offset:-4
	v_lshl_add_u64 v[64:65], v[64:65], 0, s[12:13]
	v_pk_fma_f32 v[74:75], v[66:67], v[186:187], v[76:77]
	v_pk_fma_f32 v[96:97], v[70:71], v[188:189], v[78:79]
	v_cvt_pk_bf16_f32 v74, v74, v75
	v_cvt_pk_bf16_f32 v75, v96, v97
	global_store_dwordx2 v[64:65], v[74:75], off offset:-4
	v_lshl_add_u64 v[64:65], v[64:65], 0, s[12:13]
	v_pk_fma_f32 v[74:75], v[66:67], v[190:191], v[76:77]
	v_pk_fma_f32 v[96:97], v[70:71], v[192:193], v[78:79]
	v_cvt_pk_bf16_f32 v74, v74, v75
	v_cvt_pk_bf16_f32 v75, v96, v97
	global_store_dwordx2 v[64:65], v[74:75], off offset:-4
	v_lshl_add_u64 v[64:65], v[64:65], 0, s[12:13]
	v_pk_fma_f32 v[74:75], v[66:67], v[194:195], v[76:77]
	v_pk_fma_f32 v[96:97], v[70:71], v[196:197], v[78:79]
	v_cvt_pk_bf16_f32 v74, v74, v75
	v_cvt_pk_bf16_f32 v75, v96, v97
	global_store_dwordx2 v[64:65], v[74:75], off offset:-4
	v_lshl_add_u64 v[64:65], v[64:65], 0, s[12:13]
	v_pk_fma_f32 v[74:75], v[66:67], v[198:199], v[76:77]
	v_pk_fma_f32 v[96:97], v[70:71], v[200:201], v[78:79]
	v_cvt_pk_bf16_f32 v74, v74, v75
	v_cvt_pk_bf16_f32 v75, v96, v97
	global_store_dwordx2 v[64:65], v[74:75], off offset:-4
	v_lshl_add_u64 v[64:65], v[64:65], 0, s[12:13]
	v_mul_f32_e32 v64, 0x4b800000, v95
	v_cndmask_b32_e32 v64, v95, v64, vcc
	v_rsq_f32_e32 v64, v64
	s_ashr_i32 s37, s36, 31
	s_lshl_b64 s[96:97], s[36:37], 12
	s_mov_b64 s[42:43], 8
	v_mul_f32_e32 v65, 0x45800000, v64
	v_cndmask_b32_e32 v64, v64, v65, vcc
	v_mov_b32_e32 v65, v64
	v_pk_mul_f32 v[60:61], v[60:61], v[64:65] op_sel_hi:[1,0]
	v_pk_mul_f32 v[62:63], v[62:63], v[64:65] op_sel_hi:[1,0]
	v_pk_mul_f32 v[60:61], v[0:1], v[60:61]
	v_pk_mul_f32 v[66:67], v[2:3], v[62:63]
	v_pk_fma_f32 v[62:63], v[124:125], v[60:61], v[88:89]
	v_pk_fma_f32 v[66:67], v[126:127], v[66:67], v[90:91]
	v_lshl_add_u64 v[60:61], v[112:113], 0, s[96:97]
	v_pk_add_f32 v[70:71], v[76:77], v[62:63] neg_lo:[0,1] neg_hi:[0,1]
	v_pk_add_f32 v[74:75], v[78:79], v[66:67] neg_lo:[0,1] neg_hi:[0,1]
	v_pk_fma_f32 v[76:77], v[70:71], v[178:179], v[62:63]
	v_pk_fma_f32 v[78:79], v[74:75], v[180:181], v[66:67]
	v_cvt_pk_bf16_f32 v76, v76, v77
	v_cvt_pk_bf16_f32 v77, v78, v79
	global_store_dwordx2 v[60:61], v[76:77], off offset:-4
	v_lshl_add_u64 v[60:61], v[60:61], 0, s[12:13]
	v_pk_fma_f32 v[76:77], v[70:71], v[182:183], v[62:63]
	v_pk_fma_f32 v[78:79], v[74:75], v[184:185], v[66:67]
	v_cvt_pk_bf16_f32 v76, v76, v77
	v_cvt_pk_bf16_f32 v77, v78, v79
	global_store_dwordx2 v[60:61], v[76:77], off offset:-4
	v_lshl_add_u64 v[60:61], v[60:61], 0, s[12:13]
	v_pk_fma_f32 v[76:77], v[70:71], v[186:187], v[62:63]
	v_pk_fma_f32 v[78:79], v[74:75], v[188:189], v[66:67]
	v_cvt_pk_bf16_f32 v76, v76, v77
	v_cvt_pk_bf16_f32 v77, v78, v79
	global_store_dwordx2 v[60:61], v[76:77], off offset:-4
	v_lshl_add_u64 v[60:61], v[60:61], 0, s[12:13]
	v_pk_fma_f32 v[76:77], v[70:71], v[190:191], v[62:63]
	v_pk_fma_f32 v[78:79], v[74:75], v[192:193], v[66:67]
	v_cvt_pk_bf16_f32 v76, v76, v77
	v_cvt_pk_bf16_f32 v77, v78, v79
	global_store_dwordx2 v[60:61], v[76:77], off offset:-4
	v_lshl_add_u64 v[60:61], v[60:61], 0, s[12:13]
	v_pk_fma_f32 v[76:77], v[70:71], v[194:195], v[62:63]
	v_pk_fma_f32 v[78:79], v[74:75], v[196:197], v[66:67]
	v_cvt_pk_bf16_f32 v76, v76, v77
	v_cvt_pk_bf16_f32 v77, v78, v79
	global_store_dwordx2 v[60:61], v[76:77], off offset:-4
	v_lshl_add_u64 v[60:61], v[60:61], 0, s[12:13]
	v_pk_fma_f32 v[76:77], v[70:71], v[198:199], v[62:63]
	v_pk_fma_f32 v[78:79], v[74:75], v[200:201], v[66:67]
	v_cvt_pk_bf16_f32 v76, v76, v77
	v_cvt_pk_bf16_f32 v77, v78, v79
	global_store_dwordx2 v[60:61], v[76:77], off offset:-4
	v_lshl_add_u64 v[60:61], v[60:61], 0, s[12:13]
	s_waitcnt lgkmcnt(4)
	v_pk_add_f32 v[60:61], v[130:131], v[80:81]
	s_mov_b32 s42, 0x3a000000
	s_waitcnt lgkmcnt(3)
	v_pk_add_f32 v[60:61], v[60:61], v[132:133]
	s_ashr_i32 s35, s34, 31
	s_waitcnt lgkmcnt(2)
	v_pk_add_f32 v[60:61], v[60:61], v[84:85]
	s_lshl_b64 s[92:93], s[34:35], 12
	v_pk_fma_f32 v[76:77], v[60:61], s[42:43], v[142:143] op_sel_hi:[1,0,0]
	s_nop 0
	v_mul_f32_e32 v60, 0x4b800000, v76
	v_cmp_gt_f32_e64 s[42:43], s5, v76
	v_cmp_gt_f32_e32 vcc, s5, v77
	s_nop 0
	v_cndmask_b32_e64 v60, v76, v60, s[42:43]
	v_rsq_f32_e32 v60, v60
	s_nop 0
	v_mul_f32_e32 v61, 0x45800000, v60
	v_cndmask_b32_e64 v60, v60, v61, s[42:43]
	v_mov_b32_e32 v61, v60
	v_pk_mul_f32 v[56:57], v[56:57], v[60:61] op_sel_hi:[1,0]
	v_pk_mul_f32 v[58:59], v[58:59], v[60:61] op_sel_hi:[1,0]
	v_pk_mul_f32 v[56:57], v[0:1], v[56:57]
	s_mov_b64 s[42:43], 8
	v_pk_fma_f32 v[70:71], v[124:125], v[56:57], v[88:89]
	v_pk_mul_f32 v[56:57], v[2:3], v[58:59]
	v_pk_add_f32 v[58:59], v[62:63], v[70:71] neg_lo:[0,1] neg_hi:[0,1]
	v_pk_fma_f32 v[74:75], v[126:127], v[56:57], v[90:91]
	v_lshl_add_u64 v[56:57], v[112:113], 0, s[92:93]
	v_pk_add_f32 v[62:63], v[66:67], v[74:75] neg_lo:[0,1] neg_hi:[0,1]
	v_pk_fma_f32 v[66:67], v[58:59], v[178:179], v[70:71]
	v_pk_fma_f32 v[78:79], v[62:63], v[180:181], v[74:75]
	v_cvt_pk_bf16_f32 v66, v66, v67
	v_cvt_pk_bf16_f32 v67, v78, v79
	global_store_dwordx2 v[56:57], v[66:67], off offset:-4
	v_lshl_add_u64 v[56:57], v[56:57], 0, s[12:13]
	v_pk_fma_f32 v[66:67], v[58:59], v[182:183], v[70:71]
	v_pk_fma_f32 v[78:79], v[62:63], v[184:185], v[74:75]
	v_cvt_pk_bf16_f32 v66, v66, v67
	v_cvt_pk_bf16_f32 v67, v78, v79
	global_store_dwordx2 v[56:57], v[66:67], off offset:-4
	v_lshl_add_u64 v[56:57], v[56:57], 0, s[12:13]
	v_pk_fma_f32 v[66:67], v[58:59], v[186:187], v[70:71]
	v_pk_fma_f32 v[78:79], v[62:63], v[188:189], v[74:75]
	v_cvt_pk_bf16_f32 v66, v66, v67
	v_cvt_pk_bf16_f32 v67, v78, v79
	global_store_dwordx2 v[56:57], v[66:67], off offset:-4
	v_lshl_add_u64 v[56:57], v[56:57], 0, s[12:13]
	v_pk_fma_f32 v[66:67], v[58:59], v[190:191], v[70:71]
	v_pk_fma_f32 v[78:79], v[62:63], v[192:193], v[74:75]
	v_cvt_pk_bf16_f32 v66, v66, v67
	v_cvt_pk_bf16_f32 v67, v78, v79
	global_store_dwordx2 v[56:57], v[66:67], off offset:-4
	v_lshl_add_u64 v[56:57], v[56:57], 0, s[12:13]
	v_pk_fma_f32 v[66:67], v[58:59], v[194:195], v[70:71]
	v_pk_fma_f32 v[78:79], v[62:63], v[196:197], v[74:75]
	v_cvt_pk_bf16_f32 v66, v66, v67
	v_cvt_pk_bf16_f32 v67, v78, v79
	global_store_dwordx2 v[56:57], v[66:67], off offset:-4
	v_lshl_add_u64 v[56:57], v[56:57], 0, s[12:13]
	v_pk_fma_f32 v[66:67], v[58:59], v[198:199], v[70:71]
	v_pk_fma_f32 v[78:79], v[62:63], v[200:201], v[74:75]
	v_cvt_pk_bf16_f32 v66, v66, v67
	v_cvt_pk_bf16_f32 v67, v78, v79
	global_store_dwordx2 v[56:57], v[66:67], off offset:-4
	v_lshl_add_u64 v[56:57], v[56:57], 0, s[12:13]
	v_mul_f32_e32 v56, 0x4b800000, v77
	v_cndmask_b32_e32 v56, v77, v56, vcc
	v_rsq_f32_e32 v56, v56
	s_ashr_i32 s31, s30, 31
	s_lshl_b64 s[88:89], s[30:31], 12
	s_mov_b64 s[42:43], 8
	v_mul_f32_e32 v57, 0x45800000, v56
	v_cndmask_b32_e32 v56, v56, v57, vcc
	v_mov_b32_e32 v57, v56
	v_pk_mul_f32 v[52:53], v[52:53], v[56:57] op_sel_hi:[1,0]
	v_pk_mul_f32 v[54:55], v[54:55], v[56:57] op_sel_hi:[1,0]
	v_pk_mul_f32 v[52:53], v[0:1], v[52:53]
	v_pk_mul_f32 v[54:55], v[2:3], v[54:55]
	v_pk_fma_f32 v[52:53], v[124:125], v[52:53], v[88:89]
	v_pk_fma_f32 v[58:59], v[126:127], v[54:55], v[90:91]
	v_lshl_add_u64 v[54:55], v[112:113], 0, s[88:89]
	v_pk_add_f32 v[62:63], v[70:71], v[52:53] neg_lo:[0,1] neg_hi:[0,1]
	v_pk_add_f32 v[66:67], v[74:75], v[58:59] neg_lo:[0,1] neg_hi:[0,1]
	v_pk_fma_f32 v[70:71], v[62:63], v[178:179], v[52:53]
	v_pk_fma_f32 v[74:75], v[66:67], v[180:181], v[58:59]
	v_cvt_pk_bf16_f32 v70, v70, v71
	v_cvt_pk_bf16_f32 v71, v74, v75
	global_store_dwordx2 v[54:55], v[70:71], off offset:-4
	v_lshl_add_u64 v[54:55], v[54:55], 0, s[12:13]
	v_pk_fma_f32 v[70:71], v[62:63], v[182:183], v[52:53]
	v_pk_fma_f32 v[74:75], v[66:67], v[184:185], v[58:59]
	v_cvt_pk_bf16_f32 v70, v70, v71
	v_cvt_pk_bf16_f32 v71, v74, v75
	global_store_dwordx2 v[54:55], v[70:71], off offset:-4
	v_lshl_add_u64 v[54:55], v[54:55], 0, s[12:13]
	v_pk_fma_f32 v[70:71], v[62:63], v[186:187], v[52:53]
	v_pk_fma_f32 v[74:75], v[66:67], v[188:189], v[58:59]
	v_cvt_pk_bf16_f32 v70, v70, v71
	v_cvt_pk_bf16_f32 v71, v74, v75
	global_store_dwordx2 v[54:55], v[70:71], off offset:-4
	v_lshl_add_u64 v[54:55], v[54:55], 0, s[12:13]
	v_pk_fma_f32 v[70:71], v[62:63], v[190:191], v[52:53]
	v_pk_fma_f32 v[74:75], v[66:67], v[192:193], v[58:59]
	v_cvt_pk_bf16_f32 v70, v70, v71
	v_cvt_pk_bf16_f32 v71, v74, v75
	global_store_dwordx2 v[54:55], v[70:71], off offset:-4
	v_lshl_add_u64 v[54:55], v[54:55], 0, s[12:13]
	v_pk_fma_f32 v[70:71], v[62:63], v[194:195], v[52:53]
	v_pk_fma_f32 v[74:75], v[66:67], v[196:197], v[58:59]
	v_cvt_pk_bf16_f32 v70, v70, v71
	v_cvt_pk_bf16_f32 v71, v74, v75
	global_store_dwordx2 v[54:55], v[70:71], off offset:-4
	v_lshl_add_u64 v[54:55], v[54:55], 0, s[12:13]
	v_pk_fma_f32 v[70:71], v[62:63], v[198:199], v[52:53]
	v_pk_fma_f32 v[74:75], v[66:67], v[200:201], v[58:59]
	v_cvt_pk_bf16_f32 v70, v70, v71
	v_cvt_pk_bf16_f32 v71, v74, v75
	global_store_dwordx2 v[54:55], v[70:71], off offset:-4
	v_lshl_add_u64 v[54:55], v[54:55], 0, s[12:13]
	s_waitcnt lgkmcnt(1)
	v_pk_add_f32 v[54:55], v[120:121], v[82:83]
	s_mov_b32 s42, 0x3a000000
	s_waitcnt lgkmcnt(0)
	v_pk_add_f32 v[54:55], v[54:55], v[122:123]
	s_ashr_i32 s29, s28, 31
	v_pk_add_f32 v[54:55], v[54:55], v[86:87]
	s_lshl_b64 s[84:85], s[28:29], 12
	v_pk_fma_f32 v[70:71], v[54:55], s[42:43], v[142:143] op_sel_hi:[1,0,0]
	s_nop 0
	v_mul_f32_e32 v54, 0x4b800000, v70
	v_cmp_gt_f32_e64 s[42:43], s5, v70
	v_cmp_gt_f32_e32 vcc, s5, v71
	s_nop 0
	v_cndmask_b32_e64 v54, v70, v54, s[42:43]
	v_rsq_f32_e32 v54, v54
	s_nop 0
	v_mul_f32_e32 v55, 0x45800000, v54
	v_cndmask_b32_e64 v54, v54, v55, s[42:43]
	v_mov_b32_e32 v55, v54
	v_pk_mul_f32 v[44:45], v[44:45], v[54:55] op_sel_hi:[1,0]
	v_pk_mul_f32 v[46:47], v[46:47], v[54:55] op_sel_hi:[1,0]
	v_pk_mul_f32 v[44:45], v[0:1], v[44:45]
	s_mov_b64 s[42:43], 8
	v_pk_fma_f32 v[62:63], v[124:125], v[44:45], v[88:89]
	v_pk_mul_f32 v[44:45], v[2:3], v[46:47]
	v_pk_add_f32 v[46:47], v[52:53], v[62:63] neg_lo:[0,1] neg_hi:[0,1]
	v_pk_fma_f32 v[66:67], v[126:127], v[44:45], v[90:91]
	v_lshl_add_u64 v[44:45], v[112:113], 0, s[84:85]
	v_pk_add_f32 v[52:53], v[58:59], v[66:67] neg_lo:[0,1] neg_hi:[0,1]
	v_pk_fma_f32 v[58:59], v[46:47], v[178:179], v[62:63]
	v_pk_fma_f32 v[74:75], v[52:53], v[180:181], v[66:67]
	v_cvt_pk_bf16_f32 v58, v58, v59
	v_cvt_pk_bf16_f32 v59, v74, v75
	global_store_dwordx2 v[44:45], v[58:59], off offset:-4
	v_lshl_add_u64 v[44:45], v[44:45], 0, s[12:13]
	v_pk_fma_f32 v[58:59], v[46:47], v[182:183], v[62:63]
	v_pk_fma_f32 v[74:75], v[52:53], v[184:185], v[66:67]
	v_cvt_pk_bf16_f32 v58, v58, v59
	v_cvt_pk_bf16_f32 v59, v74, v75
	global_store_dwordx2 v[44:45], v[58:59], off offset:-4
	v_lshl_add_u64 v[44:45], v[44:45], 0, s[12:13]
	v_pk_fma_f32 v[58:59], v[46:47], v[186:187], v[62:63]
	v_pk_fma_f32 v[74:75], v[52:53], v[188:189], v[66:67]
	v_cvt_pk_bf16_f32 v58, v58, v59
	v_cvt_pk_bf16_f32 v59, v74, v75
	global_store_dwordx2 v[44:45], v[58:59], off offset:-4
	v_lshl_add_u64 v[44:45], v[44:45], 0, s[12:13]
	v_pk_fma_f32 v[58:59], v[46:47], v[190:191], v[62:63]
	v_pk_fma_f32 v[74:75], v[52:53], v[192:193], v[66:67]
	v_cvt_pk_bf16_f32 v58, v58, v59
	v_cvt_pk_bf16_f32 v59, v74, v75
	global_store_dwordx2 v[44:45], v[58:59], off offset:-4
	v_lshl_add_u64 v[44:45], v[44:45], 0, s[12:13]
	v_pk_fma_f32 v[58:59], v[46:47], v[194:195], v[62:63]
	v_pk_fma_f32 v[74:75], v[52:53], v[196:197], v[66:67]
	v_cvt_pk_bf16_f32 v58, v58, v59
	v_cvt_pk_bf16_f32 v59, v74, v75
	global_store_dwordx2 v[44:45], v[58:59], off offset:-4
	v_lshl_add_u64 v[44:45], v[44:45], 0, s[12:13]
	v_pk_fma_f32 v[58:59], v[46:47], v[198:199], v[62:63]
	v_pk_fma_f32 v[74:75], v[52:53], v[200:201], v[66:67]
	v_cvt_pk_bf16_f32 v58, v58, v59
	v_cvt_pk_bf16_f32 v59, v74, v75
	global_store_dwordx2 v[44:45], v[58:59], off offset:-4
	v_lshl_add_u64 v[44:45], v[44:45], 0, s[12:13]
	v_mul_f32_e32 v44, 0x4b800000, v71
	v_cndmask_b32_e32 v44, v71, v44, vcc
	v_rsq_f32_e32 v44, v44
	s_ashr_i32 s27, s26, 31
	s_lshl_b64 s[72:73], s[26:27], 12
	s_mov_b64 s[42:43], 8
	v_mul_f32_e32 v45, 0x45800000, v44
	v_cndmask_b32_e32 v52, v44, v45, vcc
	v_mov_b32_e32 v53, v52
	v_pk_mul_f32 v[44:45], v[48:49], v[52:53] op_sel_hi:[1,0]
	v_pk_mul_f32 v[46:47], v[50:51], v[52:53] op_sel_hi:[1,0]
	v_pk_mul_f32 v[44:45], v[0:1], v[44:45]
	v_pk_mul_f32 v[46:47], v[2:3], v[46:47]
	v_pk_fma_f32 v[44:45], v[124:125], v[44:45], v[88:89]
	v_pk_fma_f32 v[46:47], v[126:127], v[46:47], v[90:91]
	v_lshl_add_u64 v[48:49], v[112:113], 0, s[72:73]
	v_pk_add_f32 v[50:51], v[62:63], v[44:45] neg_lo:[0,1] neg_hi:[0,1]
	v_pk_add_f32 v[58:59], v[66:67], v[46:47] neg_lo:[0,1] neg_hi:[0,1]
	v_pk_fma_f32 v[62:63], v[50:51], v[178:179], v[44:45]
	v_pk_fma_f32 v[66:67], v[58:59], v[180:181], v[46:47]
	v_cvt_pk_bf16_f32 v62, v62, v63
	v_cvt_pk_bf16_f32 v63, v66, v67
	global_store_dwordx2 v[48:49], v[62:63], off offset:-4
	v_lshl_add_u64 v[48:49], v[48:49], 0, s[12:13]
	v_pk_fma_f32 v[62:63], v[50:51], v[182:183], v[44:45]
	v_pk_fma_f32 v[66:67], v[58:59], v[184:185], v[46:47]
	v_cvt_pk_bf16_f32 v62, v62, v63
	v_cvt_pk_bf16_f32 v63, v66, v67
	global_store_dwordx2 v[48:49], v[62:63], off offset:-4
	v_lshl_add_u64 v[48:49], v[48:49], 0, s[12:13]
	v_pk_fma_f32 v[62:63], v[50:51], v[186:187], v[44:45]
	v_pk_fma_f32 v[66:67], v[58:59], v[188:189], v[46:47]
	v_cvt_pk_bf16_f32 v62, v62, v63
	v_cvt_pk_bf16_f32 v63, v66, v67
	global_store_dwordx2 v[48:49], v[62:63], off offset:-4
	v_lshl_add_u64 v[48:49], v[48:49], 0, s[12:13]
	v_pk_fma_f32 v[62:63], v[50:51], v[190:191], v[44:45]
	v_pk_fma_f32 v[66:67], v[58:59], v[192:193], v[46:47]
	v_cvt_pk_bf16_f32 v62, v62, v63
	v_cvt_pk_bf16_f32 v63, v66, v67
	global_store_dwordx2 v[48:49], v[62:63], off offset:-4
	v_lshl_add_u64 v[48:49], v[48:49], 0, s[12:13]
	v_pk_fma_f32 v[62:63], v[50:51], v[194:195], v[44:45]
	v_pk_fma_f32 v[66:67], v[58:59], v[196:197], v[46:47]
	v_cvt_pk_bf16_f32 v62, v62, v63
	v_cvt_pk_bf16_f32 v63, v66, v67
	global_store_dwordx2 v[48:49], v[62:63], off offset:-4
	v_lshl_add_u64 v[48:49], v[48:49], 0, s[12:13]
	v_pk_fma_f32 v[62:63], v[50:51], v[198:199], v[44:45]
	v_pk_fma_f32 v[66:67], v[58:59], v[200:201], v[46:47]
	v_cvt_pk_bf16_f32 v62, v62, v63
	v_cvt_pk_bf16_f32 v63, v66, v67
	global_store_dwordx2 v[48:49], v[62:63], off offset:-4
	v_lshl_add_u64 v[48:49], v[48:49], 0, s[12:13]
	s_cmp_lt_i32 s58, 4
	s_cselect_b64 s[56:57], -1, 0
	s_lshl_b64 s[42:43], s[58:59], 13
	s_cmp_eq_u32 s15, s49
	s_cselect_b64 s[58:59], -1, 0
	s_cmp_lg_u32 s15, s49
	s_cbranch_scc1 .LBB0_942
	s_load_dwordx2 vcc, s[0:1], 0x158
	s_and_b64 s[50:51], s[56:57], exec
	s_mov_b32 s15, 0x501c040
	s_cselect_b32 s15, s15, 0x153a4840
	s_cselect_b32 s27, s43, s55
	s_cselect_b32 s29, s42, s54
	s_waitcnt lgkmcnt(0)
	s_add_u32 s15, vcc_lo, s15
	s_addc_u32 s31, vcc_hi, 0
	s_add_u32 s50, s15, s29
	s_addc_u32 s51, s31, s27
	v_lshl_add_u64 v[48:49], v[104:105], 2, s[50:51]
	s_movk_i32 s51, 0x2000
	v_readlane_b32 s50, v219, 56
	global_store_dwordx4 v[48:49], v[44:47], off

.LBB0_945:
	v_pk_mul_f32 v[36:37], v[36:37], v[92:93]
	v_pk_mul_f32 v[38:39], v[38:39], v[92:93]
	v_pk_mul_f32 v[36:37], v[4:5], v[36:37]
	v_pk_mul_f32 v[38:39], v[6:7], v[38:39]
	s_waitcnt vmcnt(1)
	v_pk_fma_f32 v[36:37], v[36:37], v[50:51], v[44:45]
	v_pk_fma_f32 v[38:39], v[38:39], v[48:49], v[46:47]
	v_lshl_add_u64 v[58:59], v[114:115], 0, s[70:71]
	s_waitcnt vmcnt(0)
	v_pk_add_f32 v[40:41], v[40:41], v[36:37] neg_lo:[0,1] neg_hi:[0,1]
	v_pk_add_f32 v[42:43], v[42:43], v[38:39] neg_lo:[0,1] neg_hi:[0,1]
	s_mov_b64 s[40:41], 0
	v_mov_b64_e32 v[62:63], v[116:117]
	v_mov_b64_e32 v[202:203], v[116:117]
	global_load_dwordx4 v[178:181], v[202:203], off offset:-8
	v_lshl_add_u64 v[202:203], v[202:203], 0, s[10:11]
	global_load_dwordx4 v[182:185], v[202:203], off offset:-8
	v_lshl_add_u64 v[202:203], v[202:203], 0, s[10:11]
	global_load_dwordx4 v[186:189], v[202:203], off offset:-8
	v_lshl_add_u64 v[202:203], v[202:203], 0, s[10:11]
	global_load_dwordx4 v[190:193], v[202:203], off offset:-8
	v_lshl_add_u64 v[202:203], v[202:203], 0, s[10:11]
	global_load_dwordx4 v[194:197], v[202:203], off offset:-8
	v_lshl_add_u64 v[202:203], v[202:203], 0, s[10:11]
	global_load_dwordx4 v[198:201], v[202:203], off offset:-8
	v_lshl_add_u64 v[202:203], v[202:203], 0, s[10:11]
	s_waitcnt vmcnt(0)
	v_pk_fma_f32 v[66:67], v[40:41], v[178:179], v[36:37]
	v_pk_fma_f32 v[70:71], v[42:43], v[180:181], v[38:39]
	v_cvt_pk_bf16_f32 v66, v66, v67
	v_cvt_pk_bf16_f32 v67, v70, v71
	v_lshl_add_u64 v[70:71], v[58:59], 0, s[40:41]
	s_add_u32 s40, s40, 0x2400000
	v_add_co_u32_e32 v70, vcc, 0x15ab8000, v70
	s_addc_u32 s41, s41, 0
	s_nop 0
	v_addc_co_u32_e32 v71, vcc, 0, v71, vcc
	global_store_dwordx2 v[70:71], v[66:67], off
	v_pk_fma_f32 v[66:67], v[40:41], v[182:183], v[36:37]
	v_pk_fma_f32 v[70:71], v[42:43], v[184:185], v[38:39]
	v_cvt_pk_bf16_f32 v66, v66, v67
	v_cvt_pk_bf16_f32 v67, v70, v71
	v_lshl_add_u64 v[70:71], v[58:59], 0, s[40:41]
	s_add_u32 s40, s40, 0x2400000
	v_add_co_u32_e32 v70, vcc, 0x15ab8000, v70
	s_addc_u32 s41, s41, 0
	s_nop 0
	v_addc_co_u32_e32 v71, vcc, 0, v71, vcc
	global_store_dwordx2 v[70:71], v[66:67], off
	v_pk_fma_f32 v[66:67], v[40:41], v[186:187], v[36:37]
	v_pk_fma_f32 v[70:71], v[42:43], v[188:189], v[38:39]
	v_cvt_pk_bf16_f32 v66, v66, v67
	v_cvt_pk_bf16_f32 v67, v70, v71
	v_lshl_add_u64 v[70:71], v[58:59], 0, s[40:41]
	s_add_u32 s40, s40, 0x2400000
	v_add_co_u32_e32 v70, vcc, 0x15ab8000, v70
	s_addc_u32 s41, s41, 0
	s_nop 0
	v_addc_co_u32_e32 v71, vcc, 0, v71, vcc
	global_store_dwordx2 v[70:71], v[66:67], off
	v_pk_fma_f32 v[66:67], v[40:41], v[190:191], v[36:37]
	v_pk_fma_f32 v[70:71], v[42:43], v[192:193], v[38:39]
	v_cvt_pk_bf16_f32 v66, v66, v67
	v_cvt_pk_bf16_f32 v67, v70, v71
	v_lshl_add_u64 v[70:71], v[58:59], 0, s[40:41]
	s_add_u32 s40, s40, 0x2400000
	v_add_co_u32_e32 v70, vcc, 0x15ab8000, v70
	s_addc_u32 s41, s41, 0
	s_nop 0
	v_addc_co_u32_e32 v71, vcc, 0, v71, vcc
	global_store_dwordx2 v[70:71], v[66:67], off
	v_pk_fma_f32 v[66:67], v[40:41], v[194:195], v[36:37]
	v_pk_fma_f32 v[70:71], v[42:43], v[196:197], v[38:39]
	v_cvt_pk_bf16_f32 v66, v66, v67
	v_cvt_pk_bf16_f32 v67, v70, v71
	v_lshl_add_u64 v[70:71], v[58:59], 0, s[40:41]
	s_add_u32 s40, s40, 0x2400000
	v_add_co_u32_e32 v70, vcc, 0x15ab8000, v70
	s_addc_u32 s41, s41, 0
	s_nop 0
	v_addc_co_u32_e32 v71, vcc, 0, v71, vcc
	global_store_dwordx2 v[70:71], v[66:67], off
	v_pk_fma_f32 v[66:67], v[40:41], v[198:199], v[36:37]
	v_pk_fma_f32 v[70:71], v[42:43], v[200:201], v[38:39]
	v_cvt_pk_bf16_f32 v66, v66, v67
	v_cvt_pk_bf16_f32 v67, v70, v71
	v_lshl_add_u64 v[70:71], v[58:59], 0, s[40:41]
	s_add_u32 s40, s40, 0x2400000
	v_add_co_u32_e32 v70, vcc, 0x15ab8000, v70
	s_addc_u32 s41, s41, 0
	s_nop 0
	v_addc_co_u32_e32 v71, vcc, 0, v71, vcc
	global_store_dwordx2 v[70:71], v[66:67], off
	v_pk_mul_f32 v[32:33], v[32:33], v[72:73]
	v_pk_mul_f32 v[34:35], v[34:35], v[72:73]
	v_pk_mul_f32 v[32:33], v[4:5], v[32:33]
	v_pk_mul_f32 v[34:35], v[6:7], v[34:35]
	v_pk_fma_f32 v[32:33], v[32:33], v[50:51], v[44:45]
	v_pk_fma_f32 v[34:35], v[34:35], v[48:49], v[46:47]
	v_lshl_add_u64 v[40:41], v[114:115], 0, s[8:9]
	v_pk_add_f32 v[36:37], v[36:37], v[32:33] neg_lo:[0,1] neg_hi:[0,1]
	v_pk_add_f32 v[38:39], v[38:39], v[34:35] neg_lo:[0,1] neg_hi:[0,1]
	s_mov_b64 s[8:9], 0
	v_mov_b64_e32 v[42:43], v[116:117]
	v_pk_fma_f32 v[58:59], v[36:37], v[178:179], v[32:33]
	v_pk_fma_f32 v[62:63], v[38:39], v[180:181], v[34:35]
	v_cvt_pk_bf16_f32 v58, v58, v59
	v_cvt_pk_bf16_f32 v59, v62, v63
	v_lshl_add_u64 v[62:63], v[40:41], 0, s[8:9]
	s_add_u32 s8, s8, 0x2400000
	v_add_co_u32_e32 v62, vcc, 0x15ab8000, v62
	s_addc_u32 s9, s9, 0
	s_nop 0
	v_addc_co_u32_e32 v63, vcc, 0, v63, vcc
	global_store_dwordx2 v[62:63], v[58:59], off
	v_pk_fma_f32 v[58:59], v[36:37], v[182:183], v[32:33]
	v_pk_fma_f32 v[62:63], v[38:39], v[184:185], v[34:35]
	v_cvt_pk_bf16_f32 v58, v58, v59
	v_cvt_pk_bf16_f32 v59, v62, v63
	v_lshl_add_u64 v[62:63], v[40:41], 0, s[8:9]
	s_add_u32 s8, s8, 0x2400000
	v_add_co_u32_e32 v62, vcc, 0x15ab8000, v62
	s_addc_u32 s9, s9, 0
	s_nop 0
	v_addc_co_u32_e32 v63, vcc, 0, v63, vcc
	global_store_dwordx2 v[62:63], v[58:59], off
	v_pk_fma_f32 v[58:59], v[36:37], v[186:187], v[32:33]
	v_pk_fma_f32 v[62:63], v[38:39], v[188:189], v[34:35]
	v_cvt_pk_bf16_f32 v58, v58, v59
	v_cvt_pk_bf16_f32 v59, v62, v63
	v_lshl_add_u64 v[62:63], v[40:41], 0, s[8:9]
	s_add_u32 s8, s8, 0x2400000
	v_add_co_u32_e32 v62, vcc, 0x15ab8000, v62
	s_addc_u32 s9, s9, 0
	s_nop 0
	v_addc_co_u32_e32 v63, vcc, 0, v63, vcc
	global_store_dwordx2 v[62:63], v[58:59], off
	v_pk_fma_f32 v[58:59], v[36:37], v[190:191], v[32:33]
	v_pk_fma_f32 v[62:63], v[38:39], v[192:193], v[34:35]
	v_cvt_pk_bf16_f32 v58, v58, v59
	v_cvt_pk_bf16_f32 v59, v62, v63
	v_lshl_add_u64 v[62:63], v[40:41], 0, s[8:9]
	s_add_u32 s8, s8, 0x2400000
	v_add_co_u32_e32 v62, vcc, 0x15ab8000, v62
	s_addc_u32 s9, s9, 0
	s_nop 0
	v_addc_co_u32_e32 v63, vcc, 0, v63, vcc
	global_store_dwordx2 v[62:63], v[58:59], off
	v_pk_fma_f32 v[58:59], v[36:37], v[194:195], v[32:33]
	v_pk_fma_f32 v[62:63], v[38:39], v[196:197], v[34:35]
	v_cvt_pk_bf16_f32 v58, v58, v59
	v_cvt_pk_bf16_f32 v59, v62, v63
	v_lshl_add_u64 v[62:63], v[40:41], 0, s[8:9]
	s_add_u32 s8, s8, 0x2400000
	v_add_co_u32_e32 v62, vcc, 0x15ab8000, v62
	s_addc_u32 s9, s9, 0
	s_nop 0
	v_addc_co_u32_e32 v63, vcc, 0, v63, vcc
	global_store_dwordx2 v[62:63], v[58:59], off
	v_pk_fma_f32 v[58:59], v[36:37], v[198:199], v[32:33]
	v_pk_fma_f32 v[62:63], v[38:39], v[200:201], v[34:35]
	v_cvt_pk_bf16_f32 v58, v58, v59
	v_cvt_pk_bf16_f32 v59, v62, v63
	v_lshl_add_u64 v[62:63], v[40:41], 0, s[8:9]
	s_add_u32 s8, s8, 0x2400000
	v_add_co_u32_e32 v62, vcc, 0x15ab8000, v62
	s_addc_u32 s9, s9, 0
	s_nop 0
	v_addc_co_u32_e32 v63, vcc, 0, v63, vcc
	global_store_dwordx2 v[62:63], v[58:59], off
	v_pk_mul_f32 v[28:29], v[28:29], v[68:69]
	v_pk_mul_f32 v[30:31], v[30:31], v[68:69]
	v_pk_mul_f32 v[28:29], v[4:5], v[28:29]
	v_pk_mul_f32 v[30:31], v[6:7], v[30:31]
	v_pk_fma_f32 v[28:29], v[28:29], v[50:51], v[44:45]
	v_pk_fma_f32 v[30:31], v[30:31], v[48:49], v[46:47]
	v_lshl_add_u64 v[36:37], v[114:115], 0, s[90:91]
	v_pk_add_f32 v[32:33], v[32:33], v[28:29] neg_lo:[0,1] neg_hi:[0,1]
	v_pk_add_f32 v[34:35], v[34:35], v[30:31] neg_lo:[0,1] neg_hi:[0,1]
	s_mov_b64 s[8:9], 0
	v_mov_b64_e32 v[38:39], v[116:117]
	v_pk_fma_f32 v[40:41], v[32:33], v[178:179], v[28:29]
	v_pk_fma_f32 v[42:43], v[34:35], v[180:181], v[30:31]
	v_cvt_pk_bf16_f32 v40, v40, v41
	v_cvt_pk_bf16_f32 v41, v42, v43
	v_lshl_add_u64 v[42:43], v[36:37], 0, s[8:9]
	s_add_u32 s8, s8, 0x2400000
	v_add_co_u32_e32 v42, vcc, 0x15ab8000, v42
	s_addc_u32 s9, s9, 0
	s_nop 0
	v_addc_co_u32_e32 v43, vcc, 0, v43, vcc
	global_store_dwordx2 v[42:43], v[40:41], off
	v_pk_fma_f32 v[40:41], v[32:33], v[182:183], v[28:29]
	v_pk_fma_f32 v[42:43], v[34:35], v[184:185], v[30:31]
	v_cvt_pk_bf16_f32 v40, v40, v41
	v_cvt_pk_bf16_f32 v41, v42, v43
	v_lshl_add_u64 v[42:43], v[36:37], 0, s[8:9]
	s_add_u32 s8, s8, 0x2400000
	v_add_co_u32_e32 v42, vcc, 0x15ab8000, v42
	s_addc_u32 s9, s9, 0
	s_nop 0
	v_addc_co_u32_e32 v43, vcc, 0, v43, vcc
	global_store_dwordx2 v[42:43], v[40:41], off
	v_pk_fma_f32 v[40:41], v[32:33], v[186:187], v[28:29]
	v_pk_fma_f32 v[42:43], v[34:35], v[188:189], v[30:31]
	v_cvt_pk_bf16_f32 v40, v40, v41
	v_cvt_pk_bf16_f32 v41, v42, v43
	v_lshl_add_u64 v[42:43], v[36:37], 0, s[8:9]
	s_add_u32 s8, s8, 0x2400000
	v_add_co_u32_e32 v42, vcc, 0x15ab8000, v42
	s_addc_u32 s9, s9, 0
	s_nop 0
	v_addc_co_u32_e32 v43, vcc, 0, v43, vcc
	global_store_dwordx2 v[42:43], v[40:41], off
	v_pk_fma_f32 v[40:41], v[32:33], v[190:191], v[28:29]
	v_pk_fma_f32 v[42:43], v[34:35], v[192:193], v[30:31]
	v_cvt_pk_bf16_f32 v40, v40, v41
	v_cvt_pk_bf16_f32 v41, v42, v43
	v_lshl_add_u64 v[42:43], v[36:37], 0, s[8:9]
	s_add_u32 s8, s8, 0x2400000
	v_add_co_u32_e32 v42, vcc, 0x15ab8000, v42
	s_addc_u32 s9, s9, 0
	s_nop 0
	v_addc_co_u32_e32 v43, vcc, 0, v43, vcc
	global_store_dwordx2 v[42:43], v[40:41], off
	v_pk_fma_f32 v[40:41], v[32:33], v[194:195], v[28:29]
	v_pk_fma_f32 v[42:43], v[34:35], v[196:197], v[30:31]
	v_cvt_pk_bf16_f32 v40, v40, v41
	v_cvt_pk_bf16_f32 v41, v42, v43
	v_lshl_add_u64 v[42:43], v[36:37], 0, s[8:9]
	s_add_u32 s8, s8, 0x2400000
	v_add_co_u32_e32 v42, vcc, 0x15ab8000, v42
	s_addc_u32 s9, s9, 0
	s_nop 0
	v_addc_co_u32_e32 v43, vcc, 0, v43, vcc
	global_store_dwordx2 v[42:43], v[40:41], off
	v_pk_fma_f32 v[40:41], v[32:33], v[198:199], v[28:29]
	v_pk_fma_f32 v[42:43], v[34:35], v[200:201], v[30:31]
	v_cvt_pk_bf16_f32 v40, v40, v41
	v_cvt_pk_bf16_f32 v41, v42, v43
	v_lshl_add_u64 v[42:43], v[36:37], 0, s[8:9]
	s_add_u32 s8, s8, 0x2400000
	v_add_co_u32_e32 v42, vcc, 0x15ab8000, v42
	s_addc_u32 s9, s9, 0
	s_nop 0
	v_addc_co_u32_e32 v43, vcc, 0, v43, vcc
	global_store_dwordx2 v[42:43], v[40:41], off
	v_pk_mul_f32 v[24:25], v[24:25], v[64:65]
	v_pk_mul_f32 v[26:27], v[26:27], v[64:65]
	v_pk_mul_f32 v[24:25], v[4:5], v[24:25]
	v_pk_mul_f32 v[26:27], v[6:7], v[26:27]
	v_pk_fma_f32 v[24:25], v[24:25], v[50:51], v[44:45]
	v_pk_fma_f32 v[26:27], v[26:27], v[48:49], v[46:47]
	v_lshl_add_u64 v[32:33], v[114:115], 0, s[96:97]
	v_pk_add_f32 v[28:29], v[28:29], v[24:25] neg_lo:[0,1] neg_hi:[0,1]
	v_pk_add_f32 v[30:31], v[30:31], v[26:27] neg_lo:[0,1] neg_hi:[0,1]
	s_mov_b64 s[8:9], 0
	v_mov_b64_e32 v[34:35], v[116:117]
	s_mov_b64 s[90:91], s[38:39]
	v_pk_fma_f32 v[36:37], v[28:29], v[178:179], v[24:25]
	v_pk_fma_f32 v[38:39], v[30:31], v[180:181], v[26:27]
	v_cvt_pk_bf16_f32 v36, v36, v37
	v_cvt_pk_bf16_f32 v37, v38, v39
	v_lshl_add_u64 v[38:39], v[32:33], 0, s[8:9]
	s_add_u32 s8, s8, 0x2400000
	v_add_co_u32_e32 v38, vcc, 0x15ab8000, v38
	s_addc_u32 s9, s9, 0
	s_nop 0
	v_addc_co_u32_e32 v39, vcc, 0, v39, vcc
	global_store_dwordx2 v[38:39], v[36:37], off
	v_pk_fma_f32 v[36:37], v[28:29], v[182:183], v[24:25]
	v_pk_fma_f32 v[38:39], v[30:31], v[184:185], v[26:27]
	v_cvt_pk_bf16_f32 v36, v36, v37
	v_cvt_pk_bf16_f32 v37, v38, v39
	v_lshl_add_u64 v[38:39], v[32:33], 0, s[8:9]
	s_add_u32 s8, s8, 0x2400000
	v_add_co_u32_e32 v38, vcc, 0x15ab8000, v38
	s_addc_u32 s9, s9, 0
	s_nop 0
	v_addc_co_u32_e32 v39, vcc, 0, v39, vcc
	global_store_dwordx2 v[38:39], v[36:37], off
	v_pk_fma_f32 v[36:37], v[28:29], v[186:187], v[24:25]
	v_pk_fma_f32 v[38:39], v[30:31], v[188:189], v[26:27]
	v_cvt_pk_bf16_f32 v36, v36, v37
	v_cvt_pk_bf16_f32 v37, v38, v39
	v_lshl_add_u64 v[38:39], v[32:33], 0, s[8:9]
	s_add_u32 s8, s8, 0x2400000
	v_add_co_u32_e32 v38, vcc, 0x15ab8000, v38
	s_addc_u32 s9, s9, 0
	s_nop 0
	v_addc_co_u32_e32 v39, vcc, 0, v39, vcc
	global_store_dwordx2 v[38:39], v[36:37], off
	v_pk_fma_f32 v[36:37], v[28:29], v[190:191], v[24:25]
	v_pk_fma_f32 v[38:39], v[30:31], v[192:193], v[26:27]
	v_cvt_pk_bf16_f32 v36, v36, v37
	v_cvt_pk_bf16_f32 v37, v38, v39
	v_lshl_add_u64 v[38:39], v[32:33], 0, s[8:9]
	s_add_u32 s8, s8, 0x2400000
	v_add_co_u32_e32 v38, vcc, 0x15ab8000, v38
	s_addc_u32 s9, s9, 0
	s_nop 0
	v_addc_co_u32_e32 v39, vcc, 0, v39, vcc
	global_store_dwordx2 v[38:39], v[36:37], off
	v_pk_fma_f32 v[36:37], v[28:29], v[194:195], v[24:25]
	v_pk_fma_f32 v[38:39], v[30:31], v[196:197], v[26:27]
	v_cvt_pk_bf16_f32 v36, v36, v37
	v_cvt_pk_bf16_f32 v37, v38, v39
	v_lshl_add_u64 v[38:39], v[32:33], 0, s[8:9]
	s_add_u32 s8, s8, 0x2400000
	v_add_co_u32_e32 v38, vcc, 0x15ab8000, v38
	s_addc_u32 s9, s9, 0
	s_nop 0
	v_addc_co_u32_e32 v39, vcc, 0, v39, vcc
	global_store_dwordx2 v[38:39], v[36:37], off
	v_pk_fma_f32 v[36:37], v[28:29], v[198:199], v[24:25]
	v_pk_fma_f32 v[38:39], v[30:31], v[200:201], v[26:27]
	v_cvt_pk_bf16_f32 v36, v36, v37
	v_cvt_pk_bf16_f32 v37, v38, v39
	v_lshl_add_u64 v[38:39], v[32:33], 0, s[8:9]
	s_add_u32 s8, s8, 0x2400000
	v_add_co_u32_e32 v38, vcc, 0x15ab8000, v38
	s_addc_u32 s9, s9, 0
	s_nop 0
	v_addc_co_u32_e32 v39, vcc, 0, v39, vcc
	global_store_dwordx2 v[38:39], v[36:37], off
	v_pk_mul_f32 v[20:21], v[20:21], v[60:61]
	v_pk_mul_f32 v[22:23], v[22:23], v[60:61]
	v_pk_mul_f32 v[20:21], v[4:5], v[20:21]
	v_pk_mul_f32 v[22:23], v[6:7], v[22:23]
	v_pk_fma_f32 v[20:21], v[20:21], v[50:51], v[44:45]
	v_pk_fma_f32 v[22:23], v[22:23], v[48:49], v[46:47]
	v_lshl_add_u64 v[28:29], v[114:115], 0, s[92:93]
	v_pk_add_f32 v[24:25], v[24:25], v[20:21] neg_lo:[0,1] neg_hi:[0,1]
	v_pk_add_f32 v[26:27], v[26:27], v[22:23] neg_lo:[0,1] neg_hi:[0,1]
	s_mov_b64 s[8:9], 0
	v_mov_b64_e32 v[30:31], v[116:117]
	v_readlane_b32 s96, v219, 55
	v_readlane_b32 s97, v219, 59
	v_pk_fma_f32 v[32:33], v[24:25], v[178:179], v[20:21]
	v_pk_fma_f32 v[34:35], v[26:27], v[180:181], v[22:23]
	v_cvt_pk_bf16_f32 v32, v32, v33
	v_cvt_pk_bf16_f32 v33, v34, v35
	v_lshl_add_u64 v[34:35], v[28:29], 0, s[8:9]
	s_add_u32 s8, s8, 0x2400000
	v_add_co_u32_e32 v34, vcc, 0x15ab8000, v34
	s_addc_u32 s9, s9, 0
	s_nop 0
	v_addc_co_u32_e32 v35, vcc, 0, v35, vcc
	global_store_dwordx2 v[34:35], v[32:33], off
	v_pk_fma_f32 v[32:33], v[24:25], v[182:183], v[20:21]
	v_pk_fma_f32 v[34:35], v[26:27], v[184:185], v[22:23]
	v_cvt_pk_bf16_f32 v32, v32, v33
	v_cvt_pk_bf16_f32 v33, v34, v35
	v_lshl_add_u64 v[34:35], v[28:29], 0, s[8:9]
	s_add_u32 s8, s8, 0x2400000
	v_add_co_u32_e32 v34, vcc, 0x15ab8000, v34
	s_addc_u32 s9, s9, 0
	s_nop 0
	v_addc_co_u32_e32 v35, vcc, 0, v35, vcc
	global_store_dwordx2 v[34:35], v[32:33], off
	v_pk_fma_f32 v[32:33], v[24:25], v[186:187], v[20:21]
	v_pk_fma_f32 v[34:35], v[26:27], v[188:189], v[22:23]
	v_cvt_pk_bf16_f32 v32, v32, v33
	v_cvt_pk_bf16_f32 v33, v34, v35
	v_lshl_add_u64 v[34:35], v[28:29], 0, s[8:9]
	s_add_u32 s8, s8, 0x2400000
	v_add_co_u32_e32 v34, vcc, 0x15ab8000, v34
	s_addc_u32 s9, s9, 0
	s_nop 0
	v_addc_co_u32_e32 v35, vcc, 0, v35, vcc
	global_store_dwordx2 v[34:35], v[32:33], off
	v_pk_fma_f32 v[32:33], v[24:25], v[190:191], v[20:21]
	v_pk_fma_f32 v[34:35], v[26:27], v[192:193], v[22:23]
	v_cvt_pk_bf16_f32 v32, v32, v33
	v_cvt_pk_bf16_f32 v33, v34, v35
	v_lshl_add_u64 v[34:35], v[28:29], 0, s[8:9]
	s_add_u32 s8, s8, 0x2400000
	v_add_co_u32_e32 v34, vcc, 0x15ab8000, v34
	s_addc_u32 s9, s9, 0
	s_nop 0
	v_addc_co_u32_e32 v35, vcc, 0, v35, vcc
	global_store_dwordx2 v[34:35], v[32:33], off
	v_pk_fma_f32 v[32:33], v[24:25], v[194:195], v[20:21]
	v_pk_fma_f32 v[34:35], v[26:27], v[196:197], v[22:23]
	v_cvt_pk_bf16_f32 v32, v32, v33
	v_cvt_pk_bf16_f32 v33, v34, v35
	v_lshl_add_u64 v[34:35], v[28:29], 0, s[8:9]
	s_add_u32 s8, s8, 0x2400000
	v_add_co_u32_e32 v34, vcc, 0x15ab8000, v34
	s_addc_u32 s9, s9, 0
	s_nop 0
	v_addc_co_u32_e32 v35, vcc, 0, v35, vcc
	global_store_dwordx2 v[34:35], v[32:33], off
	v_pk_fma_f32 v[32:33], v[24:25], v[198:199], v[20:21]
	v_pk_fma_f32 v[34:35], v[26:27], v[200:201], v[22:23]
	v_cvt_pk_bf16_f32 v32, v32, v33
	v_cvt_pk_bf16_f32 v33, v34, v35
	v_lshl_add_u64 v[34:35], v[28:29], 0, s[8:9]
	s_add_u32 s8, s8, 0x2400000
	v_add_co_u32_e32 v34, vcc, 0x15ab8000, v34
	s_addc_u32 s9, s9, 0
	s_nop 0
	v_addc_co_u32_e32 v35, vcc, 0, v35, vcc
	global_store_dwordx2 v[34:35], v[32:33], off
	v_pk_mul_f32 v[16:17], v[16:17], v[56:57]
	v_pk_mul_f32 v[18:19], v[18:19], v[56:57]
	v_pk_mul_f32 v[16:17], v[4:5], v[16:17]
	v_pk_mul_f32 v[18:19], v[6:7], v[18:19]
	v_pk_fma_f32 v[16:17], v[16:17], v[50:51], v[44:45]
	v_pk_fma_f32 v[18:19], v[18:19], v[48:49], v[46:47]
	v_lshl_add_u64 v[24:25], v[114:115], 0, s[88:89]
	v_readlane_b32 s88, v219, 46
	v_pk_add_f32 v[20:21], v[20:21], v[16:17] neg_lo:[0,1] neg_hi:[0,1]
	v_pk_add_f32 v[22:23], v[22:23], v[18:19] neg_lo:[0,1] neg_hi:[0,1]
	s_mov_b64 s[8:9], 0
	v_mov_b64_e32 v[26:27], v[116:117]
	v_readlane_b32 s89, v219, 47
	v_readlane_b32 s92, v219, 48
	v_readlane_b32 s93, v219, 49
	v_pk_fma_f32 v[28:29], v[20:21], v[178:179], v[16:17]
	v_pk_fma_f32 v[30:31], v[22:23], v[180:181], v[18:19]
	v_cvt_pk_bf16_f32 v28, v28, v29
	v_cvt_pk_bf16_f32 v29, v30, v31
	v_lshl_add_u64 v[30:31], v[24:25], 0, s[8:9]
	s_add_u32 s8, s8, 0x2400000
	v_add_co_u32_e32 v30, vcc, 0x15ab8000, v30
	s_addc_u32 s9, s9, 0
	s_nop 0
	v_addc_co_u32_e32 v31, vcc, 0, v31, vcc
	global_store_dwordx2 v[30:31], v[28:29], off
	v_pk_fma_f32 v[28:29], v[20:21], v[182:183], v[16:17]
	v_pk_fma_f32 v[30:31], v[22:23], v[184:185], v[18:19]
	v_cvt_pk_bf16_f32 v28, v28, v29
	v_cvt_pk_bf16_f32 v29, v30, v31
	v_lshl_add_u64 v[30:31], v[24:25], 0, s[8:9]
	s_add_u32 s8, s8, 0x2400000
	v_add_co_u32_e32 v30, vcc, 0x15ab8000, v30
	s_addc_u32 s9, s9, 0
	s_nop 0
	v_addc_co_u32_e32 v31, vcc, 0, v31, vcc
	global_store_dwordx2 v[30:31], v[28:29], off
	v_pk_fma_f32 v[28:29], v[20:21], v[186:187], v[16:17]
	v_pk_fma_f32 v[30:31], v[22:23], v[188:189], v[18:19]
	v_cvt_pk_bf16_f32 v28, v28, v29
	v_cvt_pk_bf16_f32 v29, v30, v31
	v_lshl_add_u64 v[30:31], v[24:25], 0, s[8:9]
	s_add_u32 s8, s8, 0x2400000
	v_add_co_u32_e32 v30, vcc, 0x15ab8000, v30
	s_addc_u32 s9, s9, 0
	s_nop 0
	v_addc_co_u32_e32 v31, vcc, 0, v31, vcc
	global_store_dwordx2 v[30:31], v[28:29], off
	v_pk_fma_f32 v[28:29], v[20:21], v[190:191], v[16:17]
	v_pk_fma_f32 v[30:31], v[22:23], v[192:193], v[18:19]
	v_cvt_pk_bf16_f32 v28, v28, v29
	v_cvt_pk_bf16_f32 v29, v30, v31
	v_lshl_add_u64 v[30:31], v[24:25], 0, s[8:9]
	s_add_u32 s8, s8, 0x2400000
	v_add_co_u32_e32 v30, vcc, 0x15ab8000, v30
	s_addc_u32 s9, s9, 0
	s_nop 0
	v_addc_co_u32_e32 v31, vcc, 0, v31, vcc
	global_store_dwordx2 v[30:31], v[28:29], off
	v_pk_fma_f32 v[28:29], v[20:21], v[194:195], v[16:17]
	v_pk_fma_f32 v[30:31], v[22:23], v[196:197], v[18:19]
	v_cvt_pk_bf16_f32 v28, v28, v29
	v_cvt_pk_bf16_f32 v29, v30, v31
	v_lshl_add_u64 v[30:31], v[24:25], 0, s[8:9]
	s_add_u32 s8, s8, 0x2400000
	v_add_co_u32_e32 v30, vcc, 0x15ab8000, v30
	s_addc_u32 s9, s9, 0
	s_nop 0
	v_addc_co_u32_e32 v31, vcc, 0, v31, vcc
	global_store_dwordx2 v[30:31], v[28:29], off
	v_pk_fma_f32 v[28:29], v[20:21], v[198:199], v[16:17]
	v_pk_fma_f32 v[30:31], v[22:23], v[200:201], v[18:19]
	v_cvt_pk_bf16_f32 v28, v28, v29
	v_cvt_pk_bf16_f32 v29, v30, v31
	v_lshl_add_u64 v[30:31], v[24:25], 0, s[8:9]
	s_add_u32 s8, s8, 0x2400000
	v_add_co_u32_e32 v30, vcc, 0x15ab8000, v30
	s_addc_u32 s9, s9, 0
	s_nop 0
	v_addc_co_u32_e32 v31, vcc, 0, v31, vcc
	global_store_dwordx2 v[30:31], v[28:29], off
	v_pk_mul_f32 v[12:13], v[12:13], v[54:55]
	v_pk_mul_f32 v[14:15], v[14:15], v[54:55]
	v_pk_mul_f32 v[12:13], v[4:5], v[12:13]
	v_pk_mul_f32 v[14:15], v[6:7], v[14:15]
	v_pk_fma_f32 v[12:13], v[12:13], v[50:51], v[44:45]
	v_pk_fma_f32 v[14:15], v[14:15], v[48:49], v[46:47]
	v_lshl_add_u64 v[20:21], v[114:115], 0, s[84:85]
	v_pk_add_f32 v[16:17], v[16:17], v[12:13] neg_lo:[0,1] neg_hi:[0,1]
	v_pk_add_f32 v[18:19], v[18:19], v[14:15] neg_lo:[0,1] neg_hi:[0,1]
	s_mov_b64 s[8:9], 0
	v_mov_b64_e32 v[22:23], v[116:117]
	v_readlane_b32 s84, v219, 50
	v_readlane_b32 s85, v219, 51
	v_readlane_b32 s93, v219, 52
	v_pk_fma_f32 v[24:25], v[16:17], v[178:179], v[12:13]
	v_pk_fma_f32 v[26:27], v[18:19], v[180:181], v[14:15]
	v_cvt_pk_bf16_f32 v24, v24, v25
	v_cvt_pk_bf16_f32 v25, v26, v27
	v_lshl_add_u64 v[26:27], v[20:21], 0, s[8:9]
	s_add_u32 s8, s8, 0x2400000
	v_add_co_u32_e32 v26, vcc, 0x15ab8000, v26
	s_addc_u32 s9, s9, 0
	s_nop 0
	v_addc_co_u32_e32 v27, vcc, 0, v27, vcc
	global_store_dwordx2 v[26:27], v[24:25], off
	v_pk_fma_f32 v[24:25], v[16:17], v[182:183], v[12:13]
	v_pk_fma_f32 v[26:27], v[18:19], v[184:185], v[14:15]
	v_cvt_pk_bf16_f32 v24, v24, v25
	v_cvt_pk_bf16_f32 v25, v26, v27
	v_lshl_add_u64 v[26:27], v[20:21], 0, s[8:9]
	s_add_u32 s8, s8, 0x2400000
	v_add_co_u32_e32 v26, vcc, 0x15ab8000, v26
	s_addc_u32 s9, s9, 0
	s_nop 0
	v_addc_co_u32_e32 v27, vcc, 0, v27, vcc
	global_store_dwordx2 v[26:27], v[24:25], off
	v_pk_fma_f32 v[24:25], v[16:17], v[186:187], v[12:13]
	v_pk_fma_f32 v[26:27], v[18:19], v[188:189], v[14:15]
	v_cvt_pk_bf16_f32 v24, v24, v25
	v_cvt_pk_bf16_f32 v25, v26, v27
	v_lshl_add_u64 v[26:27], v[20:21], 0, s[8:9]
	s_add_u32 s8, s8, 0x2400000
	v_add_co_u32_e32 v26, vcc, 0x15ab8000, v26
	s_addc_u32 s9, s9, 0
	s_nop 0
	v_addc_co_u32_e32 v27, vcc, 0, v27, vcc
	global_store_dwordx2 v[26:27], v[24:25], off
	v_pk_fma_f32 v[24:25], v[16:17], v[190:191], v[12:13]
	v_pk_fma_f32 v[26:27], v[18:19], v[192:193], v[14:15]
	v_cvt_pk_bf16_f32 v24, v24, v25
	v_cvt_pk_bf16_f32 v25, v26, v27
	v_lshl_add_u64 v[26:27], v[20:21], 0, s[8:9]
	s_add_u32 s8, s8, 0x2400000
	v_add_co_u32_e32 v26, vcc, 0x15ab8000, v26
	s_addc_u32 s9, s9, 0
	s_nop 0
	v_addc_co_u32_e32 v27, vcc, 0, v27, vcc
	global_store_dwordx2 v[26:27], v[24:25], off
	v_pk_fma_f32 v[24:25], v[16:17], v[194:195], v[12:13]
	v_pk_fma_f32 v[26:27], v[18:19], v[196:197], v[14:15]
	v_cvt_pk_bf16_f32 v24, v24, v25
	v_cvt_pk_bf16_f32 v25, v26, v27
	v_lshl_add_u64 v[26:27], v[20:21], 0, s[8:9]
	s_add_u32 s8, s8, 0x2400000
	v_add_co_u32_e32 v26, vcc, 0x15ab8000, v26
	s_addc_u32 s9, s9, 0
	s_nop 0
	v_addc_co_u32_e32 v27, vcc, 0, v27, vcc
	global_store_dwordx2 v[26:27], v[24:25], off
	v_pk_fma_f32 v[24:25], v[16:17], v[198:199], v[12:13]
	v_pk_fma_f32 v[26:27], v[18:19], v[200:201], v[14:15]
	v_cvt_pk_bf16_f32 v24, v24, v25
	v_cvt_pk_bf16_f32 v25, v26, v27
	v_lshl_add_u64 v[26:27], v[20:21], 0, s[8:9]
	s_add_u32 s8, s8, 0x2400000
	v_add_co_u32_e32 v26, vcc, 0x15ab8000, v26
	s_addc_u32 s9, s9, 0
	s_nop 0
	v_addc_co_u32_e32 v27, vcc, 0, v27, vcc
	global_store_dwordx2 v[26:27], v[24:25], off
	v_pk_mul_f32 v[8:9], v[8:9], v[52:53]
	v_pk_mul_f32 v[10:11], v[10:11], v[52:53]
	v_pk_mul_f32 v[8:9], v[4:5], v[8:9]
	v_pk_mul_f32 v[10:11], v[6:7], v[10:11]
	v_pk_fma_f32 v[8:9], v[8:9], v[50:51], v[44:45]
	v_pk_fma_f32 v[10:11], v[10:11], v[48:49], v[46:47]
	v_lshl_add_u64 v[16:17], v[114:115], 0, s[72:73]
	v_pk_add_f32 v[12:13], v[12:13], v[8:9] neg_lo:[0,1] neg_hi:[0,1]
	v_pk_add_f32 v[14:15], v[14:15], v[10:11] neg_lo:[0,1] neg_hi:[0,1]
	s_mov_b64 s[8:9], 0
	v_mov_b64_e32 v[18:19], v[116:117]
	v_pk_fma_f32 v[20:21], v[12:13], v[178:179], v[8:9]
	v_pk_fma_f32 v[22:23], v[14:15], v[180:181], v[10:11]
	v_cvt_pk_bf16_f32 v20, v20, v21
	v_cvt_pk_bf16_f32 v21, v22, v23
	v_lshl_add_u64 v[22:23], v[16:17], 0, s[8:9]
	s_add_u32 s8, s8, 0x2400000
	v_add_co_u32_e32 v22, vcc, 0x15ab8000, v22
	s_addc_u32 s9, s9, 0
	s_nop 0
	v_addc_co_u32_e32 v23, vcc, 0, v23, vcc
	global_store_dwordx2 v[22:23], v[20:21], off
	v_pk_fma_f32 v[20:21], v[12:13], v[182:183], v[8:9]
	v_pk_fma_f32 v[22:23], v[14:15], v[184:185], v[10:11]
	v_cvt_pk_bf16_f32 v20, v20, v21
	v_cvt_pk_bf16_f32 v21, v22, v23
	v_lshl_add_u64 v[22:23], v[16:17], 0, s[8:9]
	s_add_u32 s8, s8, 0x2400000
	v_add_co_u32_e32 v22, vcc, 0x15ab8000, v22
	s_addc_u32 s9, s9, 0
	s_nop 0
	v_addc_co_u32_e32 v23, vcc, 0, v23, vcc
	global_store_dwordx2 v[22:23], v[20:21], off
	v_pk_fma_f32 v[20:21], v[12:13], v[186:187], v[8:9]
	v_pk_fma_f32 v[22:23], v[14:15], v[188:189], v[10:11]
	v_cvt_pk_bf16_f32 v20, v20, v21
	v_cvt_pk_bf16_f32 v21, v22, v23
	v_lshl_add_u64 v[22:23], v[16:17], 0, s[8:9]
	s_add_u32 s8, s8, 0x2400000
	v_add_co_u32_e32 v22, vcc, 0x15ab8000, v22
	s_addc_u32 s9, s9, 0
	s_nop 0
	v_addc_co_u32_e32 v23, vcc, 0, v23, vcc
	global_store_dwordx2 v[22:23], v[20:21], off
	v_pk_fma_f32 v[20:21], v[12:13], v[190:191], v[8:9]
	v_pk_fma_f32 v[22:23], v[14:15], v[192:193], v[10:11]
	v_cvt_pk_bf16_f32 v20, v20, v21
	v_cvt_pk_bf16_f32 v21, v22, v23
	v_lshl_add_u64 v[22:23], v[16:17], 0, s[8:9]
	s_add_u32 s8, s8, 0x2400000
	v_add_co_u32_e32 v22, vcc, 0x15ab8000, v22
	s_addc_u32 s9, s9, 0
	s_nop 0
	v_addc_co_u32_e32 v23, vcc, 0, v23, vcc
	global_store_dwordx2 v[22:23], v[20:21], off
	v_pk_fma_f32 v[20:21], v[12:13], v[194:195], v[8:9]
	v_pk_fma_f32 v[22:23], v[14:15], v[196:197], v[10:11]
	v_cvt_pk_bf16_f32 v20, v20, v21
	v_cvt_pk_bf16_f32 v21, v22, v23
	v_lshl_add_u64 v[22:23], v[16:17], 0, s[8:9]
	s_add_u32 s8, s8, 0x2400000
	v_add_co_u32_e32 v22, vcc, 0x15ab8000, v22
	s_addc_u32 s9, s9, 0
	s_nop 0
	v_addc_co_u32_e32 v23, vcc, 0, v23, vcc
	global_store_dwordx2 v[22:23], v[20:21], off
	v_pk_fma_f32 v[20:21], v[12:13], v[198:199], v[8:9]
	v_pk_fma_f32 v[22:23], v[14:15], v[200:201], v[10:11]
	v_cvt_pk_bf16_f32 v20, v20, v21
	v_cvt_pk_bf16_f32 v21, v22, v23
	v_lshl_add_u64 v[22:23], v[16:17], 0, s[8:9]
	s_add_u32 s8, s8, 0x2400000
	v_add_co_u32_e32 v22, vcc, 0x15ab8000, v22
	s_addc_u32 s9, s9, 0
	s_nop 0
	v_addc_co_u32_e32 v23, vcc, 0, v23, vcc
	global_store_dwordx2 v[22:23], v[20:21], off
	s_andn2_b64 vcc, exec, s[58:59]
	s_cbranch_vccnz .LBB0_918
	s_load_dwordx2 s[8:9], s[0:1], 0x158
	s_and_b64 s[40:41], s[56:57], exec
	s_mov_b32 s15, 0x501c040
	s_cselect_b32 s15, s15, 0x153a4840
	s_cselect_b32 s27, s43, s55
	s_cselect_b32 s29, s42, s54
	s_waitcnt lgkmcnt(0)
	s_add_u32 s8, s8, s15
	s_addc_u32 s9, s9, 0
	s_add_u32 s8, s8, s29
	s_addc_u32 s9, s9, s27
	v_lshl_add_u64 v[12:13], v[110:111], 2, s[8:9]
	global_store_dwordx4 v[12:13], v[8:11], off
	s_branch .LBB0_918
